# w_in GEMM tile order: each XCD's 192 main decode positions rotated so that the XCDs run 3 column tiles apart (12 -> 24 positions of stagger at layer 0, 6 -> 24 at layer 1)
# baseline (speedup 1.0000x reference)
.Lgi_sk_rot0:
	s_and_b32 s0, s54, 7
	s_lshr_b32 s1, s54, 3
	s_mul_i32 s57, s0, 12
	s_add_u32 s1, s1, s57
	s_cmpk_ge_u32 s1, 192
	s_cselect_b32 s57, 192, 0
	s_sub_u32 s1, s1, s57
	s_lshl_b32 s1, s1, 3
	s_or_b32 s57, s1, s0
	s_branch .Lgi_sk_dec

.Lgi_sk_rm:
	s_and_b32 s0, s57, 7
	s_lshr_b32 s1, s57, 3
	s_cmpk_ge_u32 s1, 192
	s_cbranch_scc1 .Lgi_sk_nr
	s_mul_i32 s57, s0, 18
	s_add_u32 s1, s1, s57
	s_cmpk_ge_u32 s1, 192
	s_cselect_b32 s57, 192, 0
	s_sub_u32 s1, s1, s57
.Lgi_sk_nr:
	s_mul_i32 s0, s0, 198
	s_add_u32 s57, s0, s1
	s_mul_i32 s0, s57, 0x5051
	s_lshr_b32 s0, s0, 22
	s_mul_i32 s1, s0, 204
	s_sub_u32 s1, s57, s1
	s_lshl_b32 s1, s1, 3
	s_add_u32 s57, s1, s0
